# bias staging before the norm-GEMM phases: LDS-DMA per unit instead of load-wait-ds_write (loads of all units in flight)
# baseline (speedup 1.0000x reference)
.LBB0_388:
	s_mov_b64 s[20:21], -1
	s_and_b64 vcc, exec, s[22:23]
	s_cbranch_vccz .LBB0_382
	s_and_saveexec_b64 s[20:21], s[38:39]
	s_cbranch_execz .LBB0_381
	s_ashr_i32 s14, s81, 31
	s_lshr_b32 s14, s14, 27
	s_add_i32 s14, s81, s14
	s_ashr_i32 s14, s14, 5
	s_ashr_i32 s15, s14, 31
	s_mul_i32 s15, s15, s51
	s_mul_hi_u32 s16, s14, s51
	s_add_i32 s15, s16, s15
	s_mul_i32 s14, s14, s51
	s_lshl_b32 s16, s80, 8
	s_ashr_i32 s17, s16, 31
	s_lshl_b64 s[14:15], s[14:15], 2
	s_add_u32 s22, s44, s14
	s_addc_u32 s23, s45, s15
	s_lshl_b64 s[14:15], s[16:17], 2
	s_add_u32 s14, s22, s14
	s_addc_u32 s15, s23, s15
	s_waitcnt lgkmcnt(0)
	v_lshl_add_u64 v[4:5], v[0:1], 2, s[14:15]
	v_readfirstlane_b32 s14, v2
	s_mov_b32 s15, m0
	s_mov_b32 m0, s14
	s_nop 0
	global_load_lds_dword v[4:5], off
	s_mov_b32 m0, s15
	s_branch .LBB0_381
.LBB0_391:
	s_mov_b32 s8, -1
	s_waitcnt vmcnt(0) lgkmcnt(0)
	s_barrier
	s_cmp_gt_i32 s53, 0
	v_mbcnt_lo_u32_b32 v0, s8, 0
	v_mbcnt_hi_u32_b32 v0, s8, v0
	v_add_u32_e32 v0, s33, v0
	s_cselect_b64 s[16:17], -1, 0
	s_or_b64 s[16:17], s[10:11], s[16:17]
	s_mov_b32 s15, 0
	s_mov_b64 s[18:19], -1
	v_readfirstlane_b32 s14, v0
	s_and_b64 vcc, exec, s[16:17]
	s_mov_b32 s16, s60
	s_mov_b32 s8, 0
	s_cbranch_vccnz .LBB0_396
	s_cmp_gt_i32 s53, -1
	s_cbranch_scc0 .LBB0_394
	s_mov_b32 s8, 1
	s_and_b32 s15, s3, 1
	s_branch .LBB0_395
